# on top of v6: attention PV blocks issue their eight transposed V-fragment LDS reads together, pack both P halves first, then four MFMAs behind counted lgkmcnt instead of read-wait-MFMA four times
# baseline (speedup 1.0000x reference)
; #define LAS __attribute__((address_space(3)))
; __device__ __forceinline__ unsigned pkbf(float lo, float hi) { const f32x2_t v = {lo, hi}; const bf16x2_t b = __builtin_convertvector(v, bf16x2_t); return __builtin_bit_cast(unsigned, b); }
; __device__ __forceinline__ void attn_mfma(const GAS bf16* proj, GAS bf16* part, GAS float* lse, int TOKG, const GAS float* qgain, const GAS float* kgain, const GAS float* rel_bias,
;                                           unsigned char* lds, int tid, int lane, int wave, int bid, int G) {
;     ...
;         for (int j = 0; j < 5; ++j) if (j >= nskip)
; #pragma unroll
;             for (int s2 = 0; s2 < 2; ++s2) {
;                 v4u pw; pw.x = pkbf(sc[j][8 * s2 + 0], sc[j][8 * s2 + 1]); pw.y = pkbf(sc[j][8 * s2 + 2], sc[j][8 * s2 + 3]); pw.z = pkbf(sc[j][8 * s2 + 4], sc[j][8 * s2 + 5]); pw.w = pkbf(sc[j][8 * s2 + 6], sc[j][8 * s2 + 7]);
;                 const bf16x8 pf = __builtin_bit_cast(bf16x8, pw);
;                 const int kb = 32 * wave + 32 * j + 16 * s2;
; #pragma unroll
;                 for (int dt = 0; dt < 2; ++dt) { const LAS unsigned char* vp = L + ATT_VT + vtl + kb * ATT_VSTR + 64 * dt;
;                     const v4i16_t lo = __builtin_amdgcn_ds_read_tr16_b64_v4i16((LAS v4i16_t*)vp), hi = __builtin_amdgcn_ds_read_tr16_b64_v4i16((LAS v4i16_t*)(vp + 8 * ATT_VSTR));
;                     bf16x8 vf; vf[0] = lo[0]; vf[1] = lo[1]; vf[2] = lo[2]; vf[3] = lo[3]; vf[4] = hi[0]; vf[5] = hi[1]; vf[6] = hi[2]; vf[7] = hi[3];
;                     o[dt] = __builtin_amdgcn_mfma_f32_32x32x16_bf16(vf, pf, o[dt], 0, 0, 0); } }
.LBB0_319:
	ds_read_b64_tr_b16 v[216:217], v200 offset:61440
	ds_read_b64_tr_b16 v[218:219], v200 offset:62976
	ds_read_b64_tr_b16 v[220:221], v200 offset:61504
	ds_read_b64_tr_b16 v[222:223], v200 offset:63040
	ds_read_b64_tr_b16 v[224:225], v200 offset:64512
	ds_read_b64_tr_b16 v[226:227], v201 offset:10752
	ds_read_b64_tr_b16 v[228:229], v200 offset:64576
	ds_read_b64_tr_b16 v[230:231], v201 offset:10816
	v_cvt_pk_bf16_f32 v212, v48, v49
	v_cvt_pk_bf16_f32 v213, v50, v51
	v_cvt_pk_bf16_f32 v214, v52, v53
	v_cvt_pk_bf16_f32 v215, v54, v55
	v_cvt_pk_bf16_f32 v232, v56, v57
	v_cvt_pk_bf16_f32 v233, v58, v59
	v_cvt_pk_bf16_f32 v234, v60, v61
	v_cvt_pk_bf16_f32 v235, v62, v63
	s_waitcnt lgkmcnt(6)
	v_mfma_f32_32x32x16_bf16 v[96:111], v[216:219], v[212:215], v[96:111]
	s_waitcnt lgkmcnt(4)
	v_mfma_f32_32x32x16_bf16 v[80:95], v[220:223], v[212:215], v[80:95]
	s_waitcnt lgkmcnt(2)
	v_mfma_f32_32x32x16_bf16 v[96:111], v[224:227], v[232:235], v[96:111]
	s_waitcnt lgkmcnt(0)
	v_mfma_f32_32x32x16_bf16 v[80:95], v[228:231], v[232:235], v[80:95]

; #define LAS __attribute__((address_space(3)))
; __device__ __forceinline__ unsigned pkbf(float lo, float hi) { const f32x2_t v = {lo, hi}; const bf16x2_t b = __builtin_convertvector(v, bf16x2_t); return __builtin_bit_cast(unsigned, b); }
; __device__ __forceinline__ void attn_mfma(const GAS bf16* proj, GAS bf16* part, GAS float* lse, int TOKG, const GAS float* qgain, const GAS float* kgain, const GAS float* rel_bias,
;                                           unsigned char* lds, int tid, int lane, int wave, int bid, int G) {
;     ...
;         for (int j = 0; j < 5; ++j) if (j >= nskip)
; #pragma unroll
;             for (int s2 = 0; s2 < 2; ++s2) {
;                 v4u pw; pw.x = pkbf(sc[j][8 * s2 + 0], sc[j][8 * s2 + 1]); pw.y = pkbf(sc[j][8 * s2 + 2], sc[j][8 * s2 + 3]); pw.z = pkbf(sc[j][8 * s2 + 4], sc[j][8 * s2 + 5]); pw.w = pkbf(sc[j][8 * s2 + 6], sc[j][8 * s2 + 7]);
;                 const bf16x8 pf = __builtin_bit_cast(bf16x8, pw);
;                 const int kb = 32 * wave + 32 * j + 16 * s2;
; #pragma unroll
;                 for (int dt = 0; dt < 2; ++dt) { const LAS unsigned char* vp = L + ATT_VT + vtl + kb * ATT_VSTR + 64 * dt;
;                     const v4i16_t lo = __builtin_amdgcn_ds_read_tr16_b64_v4i16((LAS v4i16_t*)vp), hi = __builtin_amdgcn_ds_read_tr16_b64_v4i16((LAS v4i16_t*)(vp + 8 * ATT_VSTR));
;                     bf16x8 vf; vf[0] = lo[0]; vf[1] = lo[1]; vf[2] = lo[2]; vf[3] = lo[3]; vf[4] = hi[0]; vf[5] = hi[1]; vf[6] = hi[2]; vf[7] = hi[3];
;                     o[dt] = __builtin_amdgcn_mfma_f32_32x32x16_bf16(vf, pf, o[dt], 0, 0, 0); } }
.LBB0_323:
	ds_read_b64_tr_b16 v[216:217], v201 offset:24576
	ds_read_b64_tr_b16 v[218:219], v201 offset:26112
	ds_read_b64_tr_b16 v[220:221], v201 offset:24640
	ds_read_b64_tr_b16 v[222:223], v201 offset:26176
	ds_read_b64_tr_b16 v[224:225], v201 offset:27648
	ds_read_b64_tr_b16 v[226:227], v201 offset:29184
	ds_read_b64_tr_b16 v[228:229], v201 offset:27712
	ds_read_b64_tr_b16 v[230:231], v201 offset:29248
	v_cvt_pk_bf16_f32 v212, v0, v1
	v_cvt_pk_bf16_f32 v213, v2, v3
	v_cvt_pk_bf16_f32 v214, v4, v5
	v_cvt_pk_bf16_f32 v215, v6, v7
	v_cvt_pk_bf16_f32 v232, v8, v9
	v_cvt_pk_bf16_f32 v233, v10, v11
	v_cvt_pk_bf16_f32 v234, v12, v13
	v_cvt_pk_bf16_f32 v235, v14, v15
	s_waitcnt lgkmcnt(6)
	v_mfma_f32_32x32x16_bf16 v[96:111], v[216:219], v[212:215], v[96:111]
	s_waitcnt lgkmcnt(4)
	v_mfma_f32_32x32x16_bf16 v[80:95], v[220:223], v[212:215], v[80:95]
	s_waitcnt lgkmcnt(2)
	v_mfma_f32_32x32x16_bf16 v[96:111], v[224:227], v[232:235], v[96:111]
	s_waitcnt lgkmcnt(0)
	v_mfma_f32_32x32x16_bf16 v[80:95], v[228:231], v[232:235], v[80:95]

; #define LAS __attribute__((address_space(3)))
; __device__ __forceinline__ unsigned pkbf(float lo, float hi) { const f32x2_t v = {lo, hi}; const bf16x2_t b = __builtin_convertvector(v, bf16x2_t); return __builtin_bit_cast(unsigned, b); }
; __device__ __forceinline__ void attn_mfma(const GAS bf16* proj, GAS bf16* part, GAS float* lse, int TOKG, const GAS float* qgain, const GAS float* kgain, const GAS float* rel_bias,
;                                           unsigned char* lds, int tid, int lane, int wave, int bid, int G) {
;     ...
;         for (int j = 0; j < 5; ++j) if (j >= nskip)
; #pragma unroll
;             for (int s2 = 0; s2 < 2; ++s2) {
;                 v4u pw; pw.x = pkbf(sc[j][8 * s2 + 0], sc[j][8 * s2 + 1]); pw.y = pkbf(sc[j][8 * s2 + 2], sc[j][8 * s2 + 3]); pw.z = pkbf(sc[j][8 * s2 + 4], sc[j][8 * s2 + 5]); pw.w = pkbf(sc[j][8 * s2 + 6], sc[j][8 * s2 + 7]);
;                 const bf16x8 pf = __builtin_bit_cast(bf16x8, pw);
;                 const int kb = 32 * wave + 32 * j + 16 * s2;
; #pragma unroll
;                 for (int dt = 0; dt < 2; ++dt) { const LAS unsigned char* vp = L + ATT_VT + vtl + kb * ATT_VSTR + 64 * dt;
;                     const v4i16_t lo = __builtin_amdgcn_ds_read_tr16_b64_v4i16((LAS v4i16_t*)vp), hi = __builtin_amdgcn_ds_read_tr16_b64_v4i16((LAS v4i16_t*)(vp + 8 * ATT_VSTR));
;                     bf16x8 vf; vf[0] = lo[0]; vf[1] = lo[1]; vf[2] = lo[2]; vf[3] = lo[3]; vf[4] = hi[0]; vf[5] = hi[1]; vf[6] = hi[2]; vf[7] = hi[3];
;                     o[dt] = __builtin_amdgcn_mfma_f32_32x32x16_bf16(vf, pf, o[dt], 0, 0, 0); } }
.LBB0_326:
	ds_read_b64_tr_b16 v[216:217], v201 offset:12288
	ds_read_b64_tr_b16 v[218:219], v201 offset:13824
	ds_read_b64_tr_b16 v[220:221], v201 offset:12352
	ds_read_b64_tr_b16 v[222:223], v201 offset:13888
	ds_read_b64_tr_b16 v[224:225], v201 offset:15360
	ds_read_b64_tr_b16 v[226:227], v201 offset:16896
	ds_read_b64_tr_b16 v[228:229], v201 offset:15424
	ds_read_b64_tr_b16 v[230:231], v201 offset:16960
	v_cvt_pk_bf16_f32 v212, v32, v33
	v_cvt_pk_bf16_f32 v213, v34, v35
	v_cvt_pk_bf16_f32 v214, v36, v37
	v_cvt_pk_bf16_f32 v215, v38, v39
	v_cvt_pk_bf16_f32 v232, v40, v41
	v_cvt_pk_bf16_f32 v233, v42, v43
	v_cvt_pk_bf16_f32 v234, v44, v45
	v_cvt_pk_bf16_f32 v235, v46, v47
	s_waitcnt lgkmcnt(6)
	v_mfma_f32_32x32x16_bf16 v[96:111], v[216:219], v[212:215], v[96:111]
	s_waitcnt lgkmcnt(4)
	v_mfma_f32_32x32x16_bf16 v[80:95], v[220:223], v[212:215], v[80:95]
	s_waitcnt lgkmcnt(2)
	v_mfma_f32_32x32x16_bf16 v[96:111], v[224:227], v[232:235], v[96:111]
	s_waitcnt lgkmcnt(0)
	v_mfma_f32_32x32x16_bf16 v[80:95], v[228:231], v[232:235], v[80:95]
	s_and_b64 vcc, exec, s[12:13]
	s_cbranch_vccnz .LBB0_322
.LBB0_327:
	ds_read_b64_tr_b16 v[216:217], v201 offset:18432
	ds_read_b64_tr_b16 v[218:219], v201 offset:19968
	ds_read_b64_tr_b16 v[220:221], v201 offset:18496
	ds_read_b64_tr_b16 v[222:223], v201 offset:20032
	ds_read_b64_tr_b16 v[224:225], v201 offset:21504
	ds_read_b64_tr_b16 v[226:227], v201 offset:23040
	ds_read_b64_tr_b16 v[228:229], v201 offset:21568
	ds_read_b64_tr_b16 v[230:231], v201 offset:23104
	v_cvt_pk_bf16_f32 v212, v16, v17
	v_cvt_pk_bf16_f32 v213, v18, v19
	v_cvt_pk_bf16_f32 v214, v20, v21
	v_cvt_pk_bf16_f32 v215, v22, v23
	v_cvt_pk_bf16_f32 v232, v24, v25
	v_cvt_pk_bf16_f32 v233, v26, v27
	v_cvt_pk_bf16_f32 v234, v28, v29
	v_cvt_pk_bf16_f32 v235, v30, v31
	s_waitcnt lgkmcnt(6)
	v_mfma_f32_32x32x16_bf16 v[96:111], v[216:219], v[212:215], v[96:111]
	s_waitcnt lgkmcnt(4)
	v_mfma_f32_32x32x16_bf16 v[80:95], v[220:223], v[212:215], v[80:95]
	s_waitcnt lgkmcnt(2)
	v_mfma_f32_32x32x16_bf16 v[96:111], v[224:227], v[232:235], v[96:111]
	s_waitcnt lgkmcnt(0)
	v_mfma_f32_32x32x16_bf16 v[80:95], v[228:231], v[232:235], v[80:95]
	s_and_b64 vcc, exec, s[10:11]
	s_cbranch_vccz .LBB0_323
	s_branch .LBB0_324
